# baseline (speedup 1.0000x reference)
.LBB0_197:
	s_mov_b32 s79, s10
	s_lshl_b32 s3, s86, 13
	s_mul_i32 s10, s86, 0xffffe100
	s_add_i32 s10, s3, s10
	v_or_b32_e32 v36, s3, v156
	v_lshl_or_b32 v44, v157, 2, s10
	v_or_b32_e32 v238, s3, v155
	v_or_b32_e32 v239, s3, v154
	v_or_b32_e32 v240, s3, v153
	ds_read_b128 v[206:209], v36 offset:24576
	ds_read_b128 v[48:51], v44 offset:51200
	ds_read_b128 v[52:55], v44 offset:51232
	ds_read_b128 v[56:59], v44 offset:51264
	ds_read_b128 v[60:63], v44 offset:51296
	ds_read_b128 v[210:213], v36 offset:28672
	ds_read_b128 v[32:35], v44 offset:51328
	ds_read_b128 v[36:39], v44 offset:51360
	ds_read_b128 v[40:43], v44 offset:51392
	ds_read_b128 v[44:47], v44 offset:51424
	ds_read_b128 v[214:217], v238 offset:24576
	ds_read_b128 v[218:221], v238 offset:28672
	ds_read_b128 v[222:225], v239 offset:24576
	ds_read_b128 v[226:229], v239 offset:28672
	ds_read_b128 v[230:233], v240 offset:24576
	s_add_i32 s81, s18, s19
	s_add_i32 s10, s81, 2
	v_add_u32_e32 v192, s78, v128
	v_add_f32_e32 v64, v190, v188
	v_add_f32_e32 v64, v186, v64
	v_add_f32_e32 v64, v189, v64
	v_add_f32_e32 v64, v184, v64
	v_add_f32_e32 v64, v187, v64
	v_add_f32_e32 v64, v183, v64
	v_add_f32_e32 v64, v185, v64
	v_add_f32_e32 v64, v171, v64
	s_waitcnt lgkmcnt(10)
	v_mfma_f32_32x32x16_bf16 v[48:63], v[206:209], v[96:99], v[48:63]
	v_add_f32_e32 v64, v180, v64
	v_add_f32_e32 v64, v170, v64
	v_add_f32_e32 v64, v172, v64
	v_exp_f32_e32 v72, v140
	v_add_f32_e32 v64, v169, v64
	v_exp_f32_e32 v73, v141
	v_add_f32_e32 v64, v182, v64
	v_exp_f32_e32 v74, v138
	v_add_f32_e32 v64, v173, v64
	ds_read_b128 v[234:237], v240 offset:28672
	s_waitcnt lgkmcnt(6)
	v_mfma_f32_32x32x16_bf16 v[32:47], v[210:213], v[96:99], v[32:47]
	v_exp_f32_e32 v75, v139
	v_add_f32_e32 v64, v181, v64
	v_exp_f32_e32 v76, v136
	v_add_f32_e32 v64, v72, v64
	v_exp_f32_e32 v77, v137
	v_add_f32_e32 v64, v73, v64
	v_exp_f32_e32 v78, v134
	v_add_f32_e32 v64, v74, v64
	v_exp_f32_e32 v79, v135
	s_waitcnt lgkmcnt(5)
	v_mfma_f32_32x32x16_bf16 v[48:63], v[214:217], v[100:103], v[48:63]
	v_add_f32_e32 v64, v75, v64
	v_exp_f32_e32 v80, v94
	v_add_f32_e32 v64, v76, v64
	v_exp_f32_e32 v81, v95
	v_add_f32_e32 v64, v77, v64
	v_exp_f32_e32 v82, v90
	v_add_f32_e32 v64, v78, v64
	v_exp_f32_e32 v83, v91
	v_add_f32_e32 v64, v79, v64
	s_waitcnt lgkmcnt(4)
	v_mfma_f32_32x32x16_bf16 v[32:47], v[218:221], v[100:103], v[32:47]
	v_exp_f32_e32 v84, v88
	v_add_f32_e32 v64, v80, v64
	v_exp_f32_e32 v85, v89
	v_add_f32_e32 v64, v81, v64
	v_exp_f32_e32 v86, v86
	v_add_f32_e32 v64, v82, v64
	v_exp_f32_e32 v87, v87
	v_add_f32_e32 v64, v83, v64
	v_add_f32_e32 v64, v84, v64
	s_waitcnt lgkmcnt(3)
	v_mfma_f32_32x32x16_bf16 v[48:63], v[222:225], v[104:107], v[48:63]
	v_add_f32_e32 v64, v85, v64
	v_add_f32_e32 v64, v86, v64
	v_add_f32_e32 v167, v87, v64
	v_mov_b32_e32 v168, v167
	v_cvt_pk_bf16_f32 v64, v188, v190
	v_cvt_pk_bf16_f32 v65, v186, v189
	v_cvt_pk_bf16_f32 v66, v184, v187
	v_cvt_pk_bf16_f32 v67, v183, v185
	v_cvt_pk_bf16_f32 v68, v171, v180
	s_waitcnt lgkmcnt(2)
	v_mfma_f32_32x32x16_bf16 v[32:47], v[226:229], v[104:107], v[32:47]
	v_cvt_pk_bf16_f32 v69, v170, v172
	v_cvt_pk_bf16_f32 v70, v169, v182
	v_cvt_pk_bf16_f32 v71, v173, v181
	v_cvt_pk_bf16_f32 v72, v72, v73
	v_cvt_pk_bf16_f32 v73, v74, v75
	v_cvt_pk_bf16_f32 v74, v76, v77
	v_cvt_pk_bf16_f32 v75, v78, v79
	v_cvt_pk_bf16_f32 v76, v80, v81
	v_cvt_pk_bf16_f32 v77, v82, v83
	s_waitcnt lgkmcnt(1)
	v_mfma_f32_32x32x16_bf16 v[48:63], v[230:233], v[108:111], v[48:63]
	v_cvt_pk_bf16_f32 v78, v84, v85
	v_cvt_pk_bf16_f32 v79, v86, v87
	s_nop 1
	v_permlane32_swap_b32_e32 v167, v168
	s_waitcnt lgkmcnt(0)
	v_mfma_f32_32x32x16_bf16 v[32:47], v[234:237], v[108:111], v[32:47]
	s_cmp_lt_i32 s10, 0
	s_cbranch_scc1 .LBB0_199
	v_add_u32_e32 v242, 0x60, v192
	v_add_u32_e32 v241, 64, v192
	v_cmp_le_i32_e32 vcc, v242, v152
	s_nop 7
	v_cndmask_b32_e32 v32, v176, v32, vcc
	v_cmp_lt_i32_e32 vcc, v241, v152
	s_nop 1
	v_cndmask_b32_e32 v49, v176, v49, vcc
	v_cmp_le_i32_e32 vcc, v241, v152
	v_add_u32_e32 v241, 0x61, v192
	s_nop 0
	v_cndmask_b32_e32 v48, v176, v48, vcc
	v_cmp_le_i32_e32 vcc, v241, v152
	v_add_u32_e32 v241, 0x42, v192
	s_nop 0
	v_cndmask_b32_e32 v33, v176, v33, vcc
	v_cmp_le_i32_e32 vcc, v241, v152
	v_add_u32_e32 v241, 0x62, v192
	s_nop 0
	v_cndmask_b32_e32 v50, v176, v50, vcc
	v_cmp_le_i32_e32 vcc, v241, v152
	v_add_u32_e32 v241, 0x43, v192
	s_nop 0
	v_cndmask_b32_e32 v34, v176, v34, vcc
	v_cmp_le_i32_e32 vcc, v241, v152
	v_add_u32_e32 v241, 0x63, v192
	s_nop 0
	v_cndmask_b32_e32 v51, v176, v51, vcc
	v_cmp_le_i32_e32 vcc, v241, v152
	v_add_u32_e32 v241, 0x48, v192
	s_nop 0
	v_cndmask_b32_e32 v35, v176, v35, vcc
	v_cmp_le_i32_e32 vcc, v241, v152
	v_add_u32_e32 v241, 0x68, v192
	s_nop 0
	v_cndmask_b32_e32 v52, v176, v52, vcc
	v_cmp_le_i32_e32 vcc, v241, v152
	v_add_u32_e32 v241, 0x49, v192
	s_nop 0
	v_cndmask_b32_e32 v36, v176, v36, vcc
	v_cmp_le_i32_e32 vcc, v241, v152
	v_add_u32_e32 v241, 0x69, v192
	s_nop 0
	v_cndmask_b32_e32 v53, v176, v53, vcc
	v_cmp_le_i32_e32 vcc, v241, v152
	v_add_u32_e32 v241, 0x4a, v192
	s_nop 0
	v_cndmask_b32_e32 v37, v176, v37, vcc
	v_cmp_le_i32_e32 vcc, v241, v152
	v_add_u32_e32 v241, 0x6a, v192
	s_nop 0
	v_cndmask_b32_e32 v54, v176, v54, vcc
	v_cmp_le_i32_e32 vcc, v241, v152
	v_add_u32_e32 v241, 0x4b, v192
	s_nop 0
	v_cndmask_b32_e32 v38, v176, v38, vcc
	v_cmp_le_i32_e32 vcc, v241, v152
	v_add_u32_e32 v241, 0x6b, v192
	s_nop 0
	v_cndmask_b32_e32 v55, v176, v55, vcc
	v_cmp_le_i32_e32 vcc, v241, v152
	v_add_u32_e32 v241, 0x50, v192
	s_nop 0
	v_cndmask_b32_e32 v39, v176, v39, vcc
	v_cmp_le_i32_e32 vcc, v241, v152
	v_add_u32_e32 v241, 0x70, v192
	s_nop 0
	v_cndmask_b32_e32 v56, v176, v56, vcc
	v_cmp_le_i32_e32 vcc, v241, v152
	v_add_u32_e32 v241, 0x51, v192
	s_nop 0
	v_cndmask_b32_e32 v40, v176, v40, vcc
	v_cmp_le_i32_e32 vcc, v241, v152
	v_add_u32_e32 v241, 0x71, v192
	s_nop 0
	v_cndmask_b32_e32 v57, v176, v57, vcc
	v_cmp_le_i32_e32 vcc, v241, v152
	v_add_u32_e32 v241, 0x52, v192
	s_nop 0
	v_cndmask_b32_e32 v41, v176, v41, vcc
	v_cmp_le_i32_e32 vcc, v241, v152
	v_add_u32_e32 v241, 0x72, v192
	s_nop 0
	v_cndmask_b32_e32 v58, v176, v58, vcc
	v_cmp_le_i32_e32 vcc, v241, v152
	v_add_u32_e32 v241, 0x53, v192
	s_nop 0
	v_cndmask_b32_e32 v42, v176, v42, vcc
	v_cmp_le_i32_e32 vcc, v241, v152
	v_add_u32_e32 v241, 0x73, v192
	s_nop 0
	v_cndmask_b32_e32 v59, v176, v59, vcc
	v_cmp_le_i32_e32 vcc, v241, v152
	v_add_u32_e32 v241, 0x58, v192
	s_nop 0
	v_cndmask_b32_e32 v43, v176, v43, vcc
	v_cmp_le_i32_e32 vcc, v241, v152
	v_add_u32_e32 v241, 0x78, v192
	s_nop 0
	v_cndmask_b32_e32 v60, v176, v60, vcc
	v_cmp_le_i32_e32 vcc, v241, v152
	v_add_u32_e32 v241, 0x59, v192
	s_nop 0
	v_cndmask_b32_e32 v44, v176, v44, vcc
	v_cmp_le_i32_e32 vcc, v241, v152
	v_add_u32_e32 v241, 0x79, v192
	s_nop 0
	v_cndmask_b32_e32 v61, v176, v61, vcc
	v_cmp_le_i32_e32 vcc, v241, v152
	v_add_u32_e32 v241, 0x5a, v192
	s_nop 0
	v_cndmask_b32_e32 v45, v176, v45, vcc
	v_cmp_le_i32_e32 vcc, v241, v152
	v_add_u32_e32 v241, 0x7a, v192
	s_nop 0
	v_cndmask_b32_e32 v62, v176, v62, vcc
	v_cmp_le_i32_e32 vcc, v241, v152
	v_add_u32_e32 v241, 0x5b, v192
	s_nop 0
	v_cndmask_b32_e32 v46, v176, v46, vcc
	v_cmp_le_i32_e32 vcc, v241, v152
	v_add_u32_e32 v241, 0x7b, v192
	s_nop 0
	v_cndmask_b32_e32 v63, v176, v63, vcc
	v_cmp_le_i32_e32 vcc, v241, v152
	s_nop 1
	v_cndmask_b32_e32 v47, v176, v47, vcc

.LBB0_201:
	s_lshl_b32 s80, s2, 13
	v_or_b32_e32 v136, s80, v151
	ds_read_b64_tr_b16 v[80:81],v136 offset:0
	ds_read_b64_tr_b16 v[82:83],v136 offset:128
	ds_read_b64_tr_b16 v[84:85],v136 offset:512
	ds_read_b64_tr_b16 v[86:87],v136 offset:640
	ds_read_b64_tr_b16 v[88:89],v136 offset:4096
	ds_read_b64_tr_b16 v[90:91],v136 offset:4224
	ds_read_b64_tr_b16 v[92:93],v136 offset:4608
	ds_read_b64_tr_b16 v[94:95],v136 offset:4736
	s_waitcnt lgkmcnt(0)
	s_nop 0
	v_mfma_f32_32x32x16_bf16 v[16:31], v[64:67], v[80:83], v[16:31]
	ds_read_b64_tr_b16 v[80:81],v136 offset:2048
	ds_read_b64_tr_b16 v[82:83],v136 offset:2176
	v_mfma_f32_32x32x16_bf16 v[16:31], v[68:71], v[84:87], v[16:31]
	ds_read_b64_tr_b16 v[84:85],v136 offset:2560
	ds_read_b64_tr_b16 v[86:87],v136 offset:2688
	v_mfma_f32_32x32x16_bf16 v[16:31], v[72:75], v[88:91], v[16:31]
	ds_read_b64_tr_b16 v[88:89],v136 offset:6144
	ds_read_b64_tr_b16 v[90:91],v136 offset:6272
	v_mfma_f32_32x32x16_bf16 v[16:31], v[76:79], v[92:95], v[16:31]
	ds_read_b64_tr_b16 v[92:93],v136 offset:6656
	ds_read_b64_tr_b16 v[94:95],v136 offset:6784
	s_waitcnt lgkmcnt(0)
	v_mfma_f32_32x32x16_bf16 v[0:15], v[64:67], v[80:83], v[0:15]
	v_max_f32_e32 v64, v48, v49
	v_max3_f32 v64, v64, v50, v51
	v_max3_f32 v64, v64, v52, v53
	v_max3_f32 v64, v64, v54, v55
	v_max3_f32 v64, v64, v56, v57
	v_mfma_f32_32x32x16_bf16 v[0:15], v[68:71], v[84:87], v[0:15]
	v_max3_f32 v64, v64, v58, v59
	v_max3_f32 v64, v64, v60, v61
	v_max3_f32 v64, v64, v62, v63
	v_max3_f32 v64, v64, v32, v33
	v_max3_f32 v64, v64, v34, v35
	v_max3_f32 v64, v64, v36, v37
	v_max3_f32 v64, v64, v38, v39
	v_mfma_f32_32x32x16_bf16 v[0:15], v[72:75], v[88:91], v[0:15]
	v_max3_f32 v64, v64, v40, v41
	v_max3_f32 v64, v64, v42, v43
	v_max3_f32 v64, v64, v44, v45
	v_max3_f32 v64, v64, v46, v47
	v_mov_b32_e32 v65, v64
	s_nop 1
	v_permlane32_swap_b32_e32 v64, v65
	v_mfma_f32_32x32x16_bf16 v[0:15], v[76:79], v[92:95], v[0:15]
	v_max_f32_e32 v64, v64, v65
	v_sub_f32_e32 v65, v64, v163
	v_mul_f32_e32 v65, 0x3e000000, v65
	s_mov_b32 s10, 0x41800000
	s_lshl_b32 s87, s79, 13
	v_cmp_ge_f32_e32 vcc, s10, v65
	v_add_u32_e32 v65, s87, v162
	s_mov_b64 s[10:11], exec
	s_cmp_lg_u64 s[22:23], 0
	s_cbranch_scc0 .Lat_h1_rare
	s_waitcnt vmcnt(5)
	ds_write_b128 v65, v[120:123]
	v_add_u32_e32 v65, s87, v161
	s_waitcnt vmcnt(4)
	ds_write_b128 v65, v[124:127] offset:24576
	s_and_saveexec_b64 s[36:37], s[6:7]
	s_cbranch_execz .LBB0_203
	v_lshl_add_u32 v65, s79, 8, v164
	s_waitcnt vmcnt(3)
	ds_write_b32 v65, v165 offset:51200
	s_branch .LBB0_203

.LBB0_203:
	s_or_b64 exec, exec, s[36:37]
	v_max_f32_e32 v136, v163, v64
	v_sub_f32_e32 v64, v163, v136
	v_mul_f32_e32 v64, 0x3e38aa3b, v64
	v_exp_f32_e32 v64, v64
	s_cmp_eq_u64 vcc, s[10:11]
	s_cselect_b64 s[10:11], -1, 0
	v_cndmask_b32_e64 v191, v64, 1.0, s[10:11]
	v_cmp_gt_f32_e32 vcc, 1.0, v191
	s_cbranch_vccz .LBB0_207
	s_and_saveexec_b64 s[36:37], s[8:9]
	ds_write_b32 v147, v191 offset:49280
	s_or_b64 exec, exec, s[36:37]
	s_waitcnt lgkmcnt(0)
	ds_read_b128 v[64:67], v145 offset:49376
	ds_read_b128 v[68:71], v145 offset:49344
	ds_read_b128 v[72:75], v145 offset:49312
	ds_read_b128 v[76:79], v145 offset:49280
	s_waitcnt lgkmcnt(3)
	v_pk_mul_f32 v[30:31], v[30:31], v[66:67]
	s_waitcnt lgkmcnt(2)
	v_pk_mul_f32 v[26:27], v[26:27], v[70:71]
	s_waitcnt lgkmcnt(1)
	v_pk_mul_f32 v[22:23], v[22:23], v[74:75]
	s_waitcnt lgkmcnt(0)
	v_pk_mul_f32 v[18:19], v[18:19], v[78:79]
	v_pk_mul_f32 v[28:29], v[28:29], v[64:65]
	v_pk_mul_f32 v[24:25], v[24:25], v[68:69]
	v_pk_mul_f32 v[20:21], v[20:21], v[72:73]
	v_pk_mul_f32 v[16:17], v[16:17], v[76:77]
	v_pk_mul_f32 v[14:15], v[14:15], v[66:67]
	v_pk_mul_f32 v[10:11], v[10:11], v[70:71]
	v_pk_mul_f32 v[6:7], v[6:7], v[74:75]
	v_pk_mul_f32 v[2:3], v[2:3], v[78:79]
	v_pk_mul_f32 v[12:13], v[12:13], v[64:65]
	v_pk_mul_f32 v[8:9], v[8:9], v[68:69]
	v_pk_mul_f32 v[4:5], v[4:5], v[72:73]
	v_pk_mul_f32 v[0:1], v[0:1], v[76:77]
.LBB0_207:
	s_waitcnt lgkmcnt(0)
	s_barrier
	s_mul_i32 s36, s79, 0xffffe100
	s_add_i32 s36, s87, s36
	v_add_u32_e32 v68, s87, v156
	v_lshl_add_u32 v76, v157, 2, s36
	v_add_u32_e32 v238, s87, v155
	v_add_u32_e32 v239, s87, v154
	v_add_u32_e32 v240, s87, v153
	ds_read_b128 v[206:209], v68 offset:24576
	ds_read_b128 v[80:83], v76 offset:51200
	ds_read_b128 v[84:87], v76 offset:51232
	ds_read_b128 v[88:91], v76 offset:51264
	ds_read_b128 v[92:95], v76 offset:51296
	ds_read_b128 v[210:213], v68 offset:28672
	ds_read_b128 v[64:67], v76 offset:51328
	ds_read_b128 v[68:71], v76 offset:51360
	ds_read_b128 v[72:75], v76 offset:51392
	ds_read_b128 v[76:79], v76 offset:51424
	ds_read_b128 v[214:217], v238 offset:24576
	ds_read_b128 v[218:221], v238 offset:28672
	ds_read_b128 v[222:225], v239 offset:24576
	ds_read_b128 v[226:229], v239 offset:28672
	ds_read_b128 v[230:233], v240 offset:24576
	s_add_i32 s81, s81, 3
	v_cndmask_b32_e64 v136, v136, v163, s[10:11]
	v_mul_f32_e32 v137, 0xbe38aa3b, v136
	v_fmamk_f32 v48, v48, 0x3e38aa3b, v137
	v_fmamk_f32 v49, v49, 0x3e38aa3b, v137
	v_fmamk_f32 v50, v50, 0x3e38aa3b, v137
	v_fmamk_f32 v51, v51, 0x3e38aa3b, v137
	v_fmamk_f32 v52, v52, 0x3e38aa3b, v137
	v_fmamk_f32 v53, v53, 0x3e38aa3b, v137
	v_fmamk_f32 v54, v54, 0x3e38aa3b, v137
	v_fmamk_f32 v55, v55, 0x3e38aa3b, v137
	v_fmamk_f32 v56, v56, 0x3e38aa3b, v137
	v_fmamk_f32 v57, v57, 0x3e38aa3b, v137
	v_fmamk_f32 v58, v58, 0x3e38aa3b, v137
	v_fmamk_f32 v59, v59, 0x3e38aa3b, v137
	s_waitcnt lgkmcnt(10)
	v_mfma_f32_32x32x16_bf16 v[80:95], v[206:209], v[96:99], v[80:95]
	v_fmamk_f32 v60, v60, 0x3e38aa3b, v137
	v_fmamk_f32 v61, v61, 0x3e38aa3b, v137
	v_fmamk_f32 v62, v62, 0x3e38aa3b, v137
	v_fmamk_f32 v63, v63, 0x3e38aa3b, v137
	v_fmamk_f32 v32, v32, 0x3e38aa3b, v137
	v_fmamk_f32 v33, v33, 0x3e38aa3b, v137
	v_fmamk_f32 v34, v34, 0x3e38aa3b, v137
	v_fmamk_f32 v35, v35, 0x3e38aa3b, v137
	v_fmamk_f32 v36, v36, 0x3e38aa3b, v137
	v_fmamk_f32 v37, v37, 0x3e38aa3b, v137
	v_fmamk_f32 v38, v38, 0x3e38aa3b, v137
	v_fmamk_f32 v39, v39, 0x3e38aa3b, v137
	v_fmamk_f32 v40, v40, 0x3e38aa3b, v137
	v_fmamk_f32 v41, v41, 0x3e38aa3b, v137
	ds_read_b128 v[234:237], v240 offset:28672
	s_waitcnt lgkmcnt(6)
	v_mfma_f32_32x32x16_bf16 v[64:79], v[210:213], v[96:99], v[64:79]
	v_fmamk_f32 v42, v42, 0x3e38aa3b, v137
	v_fmamk_f32 v43, v43, 0x3e38aa3b, v137
	v_fmamk_f32 v44, v44, 0x3e38aa3b, v137
	v_fmamk_f32 v45, v45, 0x3e38aa3b, v137
	v_fmamk_f32 v46, v46, 0x3e38aa3b, v137
	v_fmac_f32_e32 v137, 0x3e38aa3b, v47
	v_exp_f32_e32 v47, v48
	v_exp_f32_e32 v138, v49
	v_exp_f32_e32 v50, v50
	v_exp_f32_e32 v51, v51
	v_exp_f32_e32 v52, v52
	v_exp_f32_e32 v139, v32
	v_exp_f32_e32 v53, v53
	s_waitcnt lgkmcnt(5)
	v_mfma_f32_32x32x16_bf16 v[80:95], v[214:217], v[100:103], v[80:95]
	v_add_f32_e32 v32, v138, v47
	v_exp_f32_e32 v54, v54
	v_add_f32_e32 v32, v50, v32
	v_exp_f32_e32 v55, v55
	v_add_f32_e32 v32, v51, v32
	v_exp_f32_e32 v56, v56
	v_add_f32_e32 v32, v52, v32
	v_exp_f32_e32 v57, v57
	v_add_f32_e32 v32, v53, v32
	v_exp_f32_e32 v58, v58
	v_add_f32_e32 v32, v54, v32
	v_exp_f32_e32 v59, v59
	v_add_f32_e32 v32, v55, v32
	v_exp_f32_e32 v60, v60
	s_waitcnt lgkmcnt(4)
	v_mfma_f32_32x32x16_bf16 v[64:79], v[218:221], v[100:103], v[64:79]
	v_add_f32_e32 v32, v56, v32
	v_exp_f32_e32 v61, v61
	v_add_f32_e32 v32, v57, v32
	v_exp_f32_e32 v62, v62
	v_add_f32_e32 v32, v58, v32
	v_exp_f32_e32 v63, v63
	v_add_f32_e32 v32, v59, v32
	v_add_f32_e32 v32, v60, v32
	v_exp_f32_e32 v140, v33
	v_add_f32_e32 v32, v61, v32
	v_exp_f32_e32 v141, v34
	v_add_f32_e32 v32, v62, v32
	v_exp_f32_e32 v163, v35
	v_add_f32_e32 v32, v63, v32
	s_waitcnt lgkmcnt(3)
	v_mfma_f32_32x32x16_bf16 v[80:95], v[222:225], v[104:107], v[80:95]
	v_exp_f32_e32 v169, v36
	v_add_f32_e32 v32, v139, v32
	v_exp_f32_e32 v170, v37
	v_add_f32_e32 v32, v140, v32
	v_exp_f32_e32 v171, v38
	v_add_f32_e32 v32, v141, v32
	v_exp_f32_e32 v172, v39
	v_add_f32_e32 v32, v163, v32
	v_exp_f32_e32 v173, v40
	v_add_f32_e32 v32, v169, v32
	v_exp_f32_e32 v178, v41
	v_add_f32_e32 v32, v170, v32
	v_exp_f32_e32 v179, v42
	v_add_f32_e32 v32, v171, v32
	s_waitcnt lgkmcnt(2)
	v_mfma_f32_32x32x16_bf16 v[64:79], v[226:229], v[104:107], v[64:79]
	v_exp_f32_e32 v180, v43
	v_add_f32_e32 v32, v172, v32
	v_exp_f32_e32 v181, v44
	v_add_f32_e32 v32, v173, v32
	v_exp_f32_e32 v182, v45
	v_add_f32_e32 v32, v178, v32
	v_exp_f32_e32 v183, v46
	v_add_f32_e32 v32, v179, v32
	v_exp_f32_e32 v137, v137
	v_add_f32_e32 v32, v180, v32
	v_add_f32_e32 v32, v181, v32
	v_add_f32_e32 v32, v182, v32
	v_add_f32_e32 v32, v183, v32
	v_add_f32_e32 v48, v137, v32
	s_waitcnt lgkmcnt(1)
	v_mfma_f32_32x32x16_bf16 v[80:95], v[230:233], v[108:111], v[80:95]
	v_mov_b32_e32 v49, v48
	v_cvt_pk_bf16_f32 v32, v47, v138
	v_cvt_pk_bf16_f32 v33, v50, v51
	v_cvt_pk_bf16_f32 v34, v52, v53
	v_cvt_pk_bf16_f32 v35, v54, v55
	v_cvt_pk_bf16_f32 v36, v56, v57
	v_cvt_pk_bf16_f32 v37, v58, v59
	v_cvt_pk_bf16_f32 v38, v60, v61
	v_cvt_pk_bf16_f32 v39, v62, v63
	v_cvt_pk_bf16_f32 v40, v139, v140
	v_cvt_pk_bf16_f32 v41, v141, v163
	v_cvt_pk_bf16_f32 v42, v169, v170
	v_cvt_pk_bf16_f32 v43, v171, v172
	v_cvt_pk_bf16_f32 v44, v173, v178
	s_waitcnt lgkmcnt(0)
	v_mfma_f32_32x32x16_bf16 v[64:79], v[234:237], v[108:111], v[64:79]
	v_cvt_pk_bf16_f32 v45, v179, v180
	v_cvt_pk_bf16_f32 v46, v181, v182
	v_cvt_pk_bf16_f32 v47, v183, v137
	s_nop 1
	v_permlane32_swap_b32_e32 v48, v49
	s_cmp_lt_i32 s81, 0
	s_cbranch_scc1 .LBB0_209
	v_add_u32_e32 v242, 0xa0, v192
	v_add_u32_e32 v241, 0x80, v192
	v_cmp_le_i32_e32 vcc, v242, v152
	s_nop 7
	v_cndmask_b32_e32 v64, v176, v64, vcc
	v_cmp_lt_i32_e32 vcc, v241, v152
	s_nop 1
	v_cndmask_b32_e32 v81, v176, v81, vcc
	v_cmp_le_i32_e32 vcc, v241, v152
	v_add_u32_e32 v241, 0xa1, v192
	s_nop 0
	v_cndmask_b32_e32 v80, v176, v80, vcc
	v_cmp_le_i32_e32 vcc, v241, v152
	v_add_u32_e32 v241, 0x82, v192
	s_nop 0
	v_cndmask_b32_e32 v65, v176, v65, vcc
	v_cmp_le_i32_e32 vcc, v241, v152
	v_add_u32_e32 v241, 0xa2, v192
	s_nop 0
	v_cndmask_b32_e32 v82, v176, v82, vcc
	v_cmp_le_i32_e32 vcc, v241, v152
	v_add_u32_e32 v241, 0x83, v192
	s_nop 0
	v_cndmask_b32_e32 v66, v176, v66, vcc
	v_cmp_le_i32_e32 vcc, v241, v152
	v_add_u32_e32 v241, 0xa3, v192
	s_nop 0
	v_cndmask_b32_e32 v83, v176, v83, vcc
	v_cmp_le_i32_e32 vcc, v241, v152
	v_add_u32_e32 v241, 0x88, v192
	s_nop 0
	v_cndmask_b32_e32 v67, v176, v67, vcc
	v_cmp_le_i32_e32 vcc, v241, v152
	v_add_u32_e32 v241, 0xa8, v192
	s_nop 0
	v_cndmask_b32_e32 v84, v176, v84, vcc
	v_cmp_le_i32_e32 vcc, v241, v152
	v_add_u32_e32 v241, 0x89, v192
	s_nop 0
	v_cndmask_b32_e32 v68, v176, v68, vcc
	v_cmp_le_i32_e32 vcc, v241, v152
	v_add_u32_e32 v241, 0xa9, v192
	s_nop 0
	v_cndmask_b32_e32 v85, v176, v85, vcc
	v_cmp_le_i32_e32 vcc, v241, v152
	v_add_u32_e32 v241, 0x8a, v192
	s_nop 0
	v_cndmask_b32_e32 v69, v176, v69, vcc
	v_cmp_le_i32_e32 vcc, v241, v152
	v_add_u32_e32 v241, 0xaa, v192
	s_nop 0
	v_cndmask_b32_e32 v86, v176, v86, vcc
	v_cmp_le_i32_e32 vcc, v241, v152
	v_add_u32_e32 v241, 0x8b, v192
	s_nop 0
	v_cndmask_b32_e32 v70, v176, v70, vcc
	v_cmp_le_i32_e32 vcc, v241, v152
	v_add_u32_e32 v241, 0xab, v192
	s_nop 0
	v_cndmask_b32_e32 v87, v176, v87, vcc
	v_cmp_le_i32_e32 vcc, v241, v152
	v_add_u32_e32 v241, 0x90, v192
	s_nop 0
	v_cndmask_b32_e32 v71, v176, v71, vcc
	v_cmp_le_i32_e32 vcc, v241, v152
	v_add_u32_e32 v241, 0xb0, v192
	s_nop 0
	v_cndmask_b32_e32 v88, v176, v88, vcc
	v_cmp_le_i32_e32 vcc, v241, v152
	v_add_u32_e32 v241, 0x91, v192
	s_nop 0
	v_cndmask_b32_e32 v72, v176, v72, vcc
	v_cmp_le_i32_e32 vcc, v241, v152
	v_add_u32_e32 v241, 0xb1, v192
	s_nop 0
	v_cndmask_b32_e32 v89, v176, v89, vcc
	v_cmp_le_i32_e32 vcc, v241, v152
	v_add_u32_e32 v241, 0x92, v192
	s_nop 0
	v_cndmask_b32_e32 v73, v176, v73, vcc
	v_cmp_le_i32_e32 vcc, v241, v152
	v_add_u32_e32 v241, 0xb2, v192
	s_nop 0
	v_cndmask_b32_e32 v90, v176, v90, vcc
	v_cmp_le_i32_e32 vcc, v241, v152
	v_add_u32_e32 v241, 0x93, v192
	s_nop 0
	v_cndmask_b32_e32 v74, v176, v74, vcc
	v_cmp_le_i32_e32 vcc, v241, v152
	v_add_u32_e32 v241, 0xb3, v192
	s_nop 0
	v_cndmask_b32_e32 v91, v176, v91, vcc
	v_cmp_le_i32_e32 vcc, v241, v152
	v_add_u32_e32 v241, 0x98, v192
	s_nop 0
	v_cndmask_b32_e32 v75, v176, v75, vcc
	v_cmp_le_i32_e32 vcc, v241, v152
	v_add_u32_e32 v241, 0xb8, v192
	s_nop 0
	v_cndmask_b32_e32 v92, v176, v92, vcc
	v_cmp_le_i32_e32 vcc, v241, v152
	v_add_u32_e32 v241, 0x99, v192
	s_nop 0
	v_cndmask_b32_e32 v76, v176, v76, vcc
	v_cmp_le_i32_e32 vcc, v241, v152
	v_add_u32_e32 v241, 0xb9, v192
	s_nop 0
	v_cndmask_b32_e32 v93, v176, v93, vcc
	v_cmp_le_i32_e32 vcc, v241, v152
	v_add_u32_e32 v241, 0x9a, v192
	s_nop 0
	v_cndmask_b32_e32 v77, v176, v77, vcc
	v_cmp_le_i32_e32 vcc, v241, v152
	v_add_u32_e32 v241, 0xba, v192
	s_nop 0
	v_cndmask_b32_e32 v94, v176, v94, vcc
	v_cmp_le_i32_e32 vcc, v241, v152
	v_add_u32_e32 v241, 0x9b, v192
	s_nop 0
	v_cndmask_b32_e32 v78, v176, v78, vcc
	v_cmp_le_i32_e32 vcc, v241, v152
	v_add_u32_e32 v241, 0xbb, v192
	s_nop 0
	v_cndmask_b32_e32 v95, v176, v95, vcc
	v_cmp_le_i32_e32 vcc, v241, v152
	s_nop 1
	v_cndmask_b32_e32 v79, v176, v79, vcc

.LBB0_211:
	v_add_u32_e32 v62, s3, v151
	ds_read_b64_tr_b16 v[50:51],v62 offset:0
	ds_read_b64_tr_b16 v[52:53],v62 offset:128
	ds_read_b64_tr_b16 v[54:55],v62 offset:512
	ds_read_b64_tr_b16 v[56:57],v62 offset:640
	ds_read_b64_tr_b16 v[58:59],v62 offset:4096
	ds_read_b64_tr_b16 v[60:61],v62 offset:4224
	ds_read_b64_tr_b16 v[138:139],v62 offset:4608
	ds_read_b64_tr_b16 v[140:141],v62 offset:4736
	s_waitcnt lgkmcnt(0)
	s_nop 0
	v_mfma_f32_32x32x16_bf16 v[16:31], v[32:35], v[50:53], v[16:31]
	ds_read_b64_tr_b16 v[50:51],v62 offset:2048
	ds_read_b64_tr_b16 v[52:53],v62 offset:2176
	v_mfma_f32_32x32x16_bf16 v[16:31], v[36:39], v[54:57], v[16:31]
	ds_read_b64_tr_b16 v[54:55],v62 offset:2560
	ds_read_b64_tr_b16 v[56:57],v62 offset:2688
	v_mfma_f32_32x32x16_bf16 v[16:31], v[40:43], v[58:61], v[16:31]
	ds_read_b64_tr_b16 v[58:59],v62 offset:6144
	ds_read_b64_tr_b16 v[60:61],v62 offset:6272
	v_mfma_f32_32x32x16_bf16 v[16:31], v[44:47], v[138:141], v[16:31]
	ds_read_b64_tr_b16 v[138:139],v62 offset:6656
	ds_read_b64_tr_b16 v[140:141],v62 offset:6784
	s_waitcnt lgkmcnt(0)
	v_mfma_f32_32x32x16_bf16 v[0:15], v[32:35], v[50:53], v[0:15]
	v_max_f32_e32 v32, v80, v81
	v_max3_f32 v32, v32, v82, v83
	v_max3_f32 v32, v32, v84, v85
	v_max3_f32 v32, v32, v86, v87
	v_max3_f32 v32, v32, v88, v89
	v_mfma_f32_32x32x16_bf16 v[0:15], v[36:39], v[54:57], v[0:15]
	v_max3_f32 v32, v32, v90, v91
	v_max3_f32 v32, v32, v92, v93
	v_max3_f32 v32, v32, v94, v95
	v_max3_f32 v32, v32, v64, v65
	v_max3_f32 v32, v32, v66, v67
	v_max3_f32 v32, v32, v68, v69
	v_max3_f32 v32, v32, v70, v71
	v_mfma_f32_32x32x16_bf16 v[0:15], v[40:43], v[58:61], v[0:15]
	v_max3_f32 v32, v32, v72, v73
	v_max3_f32 v32, v32, v74, v75
	v_max3_f32 v32, v32, v76, v77
	v_max3_f32 v32, v32, v78, v79
	v_mov_b32_e32 v33, v32
	s_nop 1
	v_permlane32_swap_b32_e32 v32, v33
	v_mfma_f32_32x32x16_bf16 v[0:15], v[44:47], v[138:141], v[0:15]
	v_max_f32_e32 v32, v32, v33
	v_sub_f32_e32 v33, v32, v136
	v_mul_f32_e32 v33, 0x3e000000, v33
	s_mov_b32 s3, 0x41800000
	v_cmp_ge_f32_e32 vcc, s3, v33
	s_cmp_eq_u64 vcc, exec
	s_cselect_b64 s[10:11], -1, 0
	s_andn2_b64 vcc, exec, s[22:23]
	s_cbranch_vccnz .LBB0_215
	s_cmp_ge_i32 s36, s77
	s_cbranch_scc1 .Lat_h2_rare
	v_add_u32_e32 v33, s80, v162
	s_waitcnt vmcnt(5)
	ds_write_b128 v33, v[112:115]
	v_add_u32_e32 v33, s80, v161
	s_waitcnt vmcnt(4)
	ds_write_b128 v33, v[116:119] offset:24576
	s_and_saveexec_b64 s[22:23], s[6:7]
	s_cbranch_execz .LBB0_214
	v_lshl_add_u32 v33, s2, 8, v164
	s_waitcnt vmcnt(3)
	ds_write_b32 v33, v160 offset:51200
	s_branch .LBB0_214

.LBB0_215:
	v_max_f32_e32 v32, v136, v32
	v_sub_f32_e32 v33, v136, v32
	v_mul_f32_e32 v33, 0x3e38aa3b, v33
	v_exp_f32_e32 v33, v33
	s_nop 0
	v_cndmask_b32_e64 v33, v33, 1.0, s[10:11]
	v_cmp_gt_f32_e32 vcc, 1.0, v33
	s_cbranch_vccz .LBB0_219
	s_and_saveexec_b64 s[22:23], s[8:9]
	ds_write_b32 v147, v33 offset:49280
	s_or_b64 exec, exec, s[22:23]
	s_waitcnt lgkmcnt(0)
	ds_read_b128 v[34:37], v145 offset:49376
	ds_read_b128 v[38:41], v145 offset:49344
	ds_read_b128 v[42:45], v145 offset:49312
	ds_read_b128 v[50:53], v145 offset:49280
	s_waitcnt lgkmcnt(3)
	v_pk_mul_f32 v[30:31], v[30:31], v[36:37]
	s_waitcnt lgkmcnt(2)
	v_pk_mul_f32 v[26:27], v[26:27], v[40:41]
	s_waitcnt lgkmcnt(1)
	v_pk_mul_f32 v[22:23], v[22:23], v[44:45]
	s_waitcnt lgkmcnt(0)
	v_pk_mul_f32 v[18:19], v[18:19], v[52:53]
	v_pk_mul_f32 v[28:29], v[28:29], v[34:35]
	v_pk_mul_f32 v[24:25], v[24:25], v[38:39]
	v_pk_mul_f32 v[20:21], v[20:21], v[42:43]
	v_pk_mul_f32 v[16:17], v[16:17], v[50:51]
	v_pk_mul_f32 v[14:15], v[14:15], v[36:37]
	v_pk_mul_f32 v[10:11], v[10:11], v[40:41]
	v_pk_mul_f32 v[6:7], v[6:7], v[44:45]
	v_pk_mul_f32 v[2:3], v[2:3], v[52:53]
	v_pk_mul_f32 v[12:13], v[12:13], v[34:35]
	v_pk_mul_f32 v[8:9], v[8:9], v[38:39]
	v_pk_mul_f32 v[4:5], v[4:5], v[42:43]
	v_pk_mul_f32 v[0:1], v[0:1], v[50:51]
